# v4: v2 + attention: dilated loop issues all K/V fragment LDS reads ahead of their MFMAs (free VGPRs 210-249), stick-breaking loop accumulates O in place (no 64-register copy per step)
# speedup vs baseline: 1.0014x; 1.0014x over previous
.LBB0_385:
	s_or_b64 exec, exec, s[90:91]
	s_lshr_b32 s1, s88, 6
	s_and_b32 s1, s1, 0x3fffffc
	s_sub_i32 s1, s95, s1
	s_and_b32 s1, s1, 15
	s_lshl_b32 s1, s1, 3
	s_or_b32 s1, s1, 6
	s_mov_b32 s4, 0x10000
	s_mov_b32 s69, 8
	v_readlane_b32 s76, v254, 41
	s_waitcnt vmcnt(0)
	v_mov_b64_e32 v[4:5], v[116:117]
	v_mov_b64_e32 v[6:7], v[118:119]
	v_mov_b64_e32 v[8:9], v[120:121]
	v_mov_b64_e32 v[10:11], v[122:123]
	v_mov_b64_e32 v[12:13], v[124:125]
	v_mov_b64_e32 v[14:15], v[126:127]
	v_mov_b64_e32 v[16:17], v[128:129]
	v_mov_b64_e32 v[18:19], v[130:131]
	v_mov_b64_e32 v[20:21], v[100:101]
	v_mov_b64_e32 v[22:23], v[102:103]
	v_mov_b64_e32 v[24:25], v[104:105]
	v_mov_b64_e32 v[26:27], v[106:107]
	v_mov_b64_e32 v[28:29], v[108:109]
	v_mov_b64_e32 v[30:31], v[110:111]
	v_mov_b64_e32 v[32:33], v[112:113]
	v_mov_b64_e32 v[34:35], v[114:115]
	v_mov_b64_e32 v[36:37], v[68:69]
	v_mov_b64_e32 v[38:39], v[70:71]
	v_mov_b64_e32 v[40:41], v[72:73]
	v_mov_b64_e32 v[42:43], v[74:75]
	v_mov_b64_e32 v[44:45], v[76:77]
	v_mov_b64_e32 v[46:47], v[78:79]
	v_mov_b64_e32 v[48:49], v[80:81]
	v_mov_b64_e32 v[50:51], v[82:83]
	v_mov_b64_e32 v[52:53], v[84:85]
	v_mov_b64_e32 v[54:55], v[86:87]
	v_mov_b64_e32 v[56:57], v[88:89]
	v_mov_b64_e32 v[58:59], v[90:91]
	v_mov_b64_e32 v[60:61], v[92:93]
	v_mov_b64_e32 v[62:63], v[94:95]
	v_mov_b64_e32 v[64:65], v[96:97]
	v_mov_b64_e32 v[66:67], v[98:99]
	s_branch .LBB0_388

.LBB0_388:
	s_and_b32 s46, s69, 8
	s_xor_b32 s66, s46, 8
	s_add_i32 s67, 0, 0x10000
	s_lshl_b32 s66, s66, 2
	s_add_i32 s66, s67, s66
	v_mov_b32_e32 v1, s66
	s_xor_b32 s66, s46, 9
	s_lshl_b32 s66, s66, 2
	s_waitcnt vmcnt(4)
	s_add_i32 s66, s67, s66
	s_waitcnt lgkmcnt(0)
	s_barrier
	v_mov_b32_e32 v2, s66
	s_xor_b32 s66, s46, 10
	ds_read_b32 v1, v1
	ds_read_b32 v2, v2
	s_lshl_b32 s66, s66, 2
	s_add_i32 s66, s67, s66
	v_mov_b32_e32 v228, s66
	s_xor_b32 s66, s46, 11
	ds_read_b32 v68, v228
	s_lshl_b32 s66, s66, 2
	s_add_i32 s66, s67, s66
	s_waitcnt lgkmcnt(0)
	v_and_b32_e32 v1, v1, v2
	v_mov_b32_e32 v2, s66
	s_xor_b32 s66, s46, 12
	s_lshl_b32 s66, s66, 2
	s_add_i32 s66, s67, s66
	v_and_b32_e32 v1, v1, v68
	v_mov_b32_e32 v68, s66
	s_xor_b32 s66, s46, 13
	s_lshl_b32 s66, s66, 2
	s_add_i32 s66, s67, s66
	v_mov_b32_e32 v69, s66
	s_xor_b32 s66, s46, 14
	s_lshl_b32 s66, s66, 2
	s_add_i32 s66, s67, s66
	ds_read_b32 v2, v2
	v_mov_b32_e32 v70, s66
	s_xor_b32 s66, s46, 15
	ds_read_b32 v68, v68
	s_lshl_b32 s66, s66, 2
	ds_read_b32 v69, v69
	s_add_i32 s66, s67, s66
	ds_read_b32 v70, v70
	v_mov_b32_e32 v71, s66
	ds_read_b32 v71, v71
	s_waitcnt lgkmcnt(0)
	v_and_b32_e32 v1, v1, v2
	s_waitcnt lgkmcnt(3)
	v_and_b32_e32 v1, v1, v68
	s_waitcnt lgkmcnt(2)
	v_and_b32_e32 v1, v1, v69
	s_waitcnt lgkmcnt(1)
	v_and_b32_e32 v1, v1, v70
	s_waitcnt lgkmcnt(0)
	v_and_b32_e32 v1, v1, v71
	v_and_b32_e32 v1, 1, v1
	v_cmp_eq_u32_e32 vcc, 1, v1
	s_mov_b64 s[90:91], -1
	s_and_b64 vcc, exec, vcc
	s_cbranch_vccnz .LBB0_387
	s_max_i32 s66, s1, 3
	s_lshl_b32 s66, s66, 5
	s_addk_i32 s66, 0xffa0
	s_and_b32 s90, s4, 0xc000
	s_ashr_i32 s67, s66, 31
	s_lshl_b64 s[66:67], s[66:67], 12
	s_add_i32 s90, s94, s90
	v_lshl_add_u64 v[68:69], v[174:175], 0, s[66:67]
	s_mov_b32 m0, s90
	s_nop 0
	global_load_lds_dwordx4 v[68:69], off
	v_lshl_add_u64 v[68:69], v[176:177], 0, s[66:67]
	s_add_i32 m0, s90, 0x2000
	s_cmp_gt_i32 s1, s79
	global_load_lds_dwordx4 v[68:69], off
	s_cselect_b64 s[66:67], -1, 0
	s_or_b64 s[66:67], s[66:67], s[86:87]
	s_and_b64 vcc, exec, s[66:67]
	s_cbranch_vccnz .LBB0_394
	s_add_i32 s66, s4, 0xffff4000
	s_and_b32 s66, s66, 0xc000
	s_add_i32 s90, s66, 0
	v_add_u32_e32 v1, s90, v181
	v_add_u32_e32 v2, v1, v183
	ds_read_b128 v[68:71], v2
	v_add_u32_e32 v2, v1, v184
	ds_read_b128 v[84:87], v2
	v_add_u32_e32 v2, v1, v185
	s_cmp_eq_u32 s76, 0
	s_cselect_b64 s[86:87], -1, 0
	s_cmp_lg_u32 s76, 0
	s_waitcnt lgkmcnt(0)
	v_mfma_f32_32x32x16_bf16 v[68:83], v[68:71], v[132:135], 0
	v_mfma_f32_32x32x16_bf16 v[68:83], v[84:87], v[136:139], v[68:83]
	ds_read_b128 v[84:87], v2
	v_add_u32_e32 v2, v1, v186
	ds_read_b128 v[88:91], v2
	v_add_u32_e32 v2, v1, v187
	s_waitcnt lgkmcnt(0)
	v_mfma_f32_32x32x16_bf16 v[68:83], v[84:87], v[140:143], v[68:83]
	ds_read_b128 v[84:87], v2
	v_add_u32_e32 v2, v1, v188
	v_mfma_f32_32x32x16_bf16 v[68:83], v[88:91], v[144:147], v[68:83]
	ds_read_b128 v[88:91], v2
	v_add_u32_e32 v2, v1, v189
	v_add_u32_e32 v1, v1, v190
	s_waitcnt lgkmcnt(0)
	v_mfma_f32_32x32x16_bf16 v[68:83], v[84:87], v[148:151], v[68:83]
	ds_read_b128 v[84:87], v2
	v_mfma_f32_32x32x16_bf16 v[68:83], v[88:91], v[152:155], v[68:83]
	ds_read_b128 v[88:91], v1
	s_waitcnt lgkmcnt(0)
	v_mfma_f32_32x32x16_bf16 v[68:83], v[84:87], v[156:159], v[68:83]
	v_mfma_f32_32x32x16_bf16 v[68:83], v[88:91], v[160:163], v[68:83]
	s_nop 11
	v_exp_f32_e64 v1, -|v68|
	v_exp_f32_e64 v84, -|v69|
	v_exp_f32_e64 v88, -|v71|
	v_exp_f32_e64 v86, -|v70|
	v_exp_f32_e64 v90, -|v72|
	v_exp_f32_e64 v92, -|v73|
	v_add_f32_e32 v1, 1.0, v1
	v_add_f32_e32 v84, 1.0, v84
	v_add_f32_e32 v88, 1.0, v88
	v_log_f32_e32 v1, v1
	v_exp_f32_e64 v94, -|v74|
	v_add_f32_e32 v86, 1.0, v86
	v_add_f32_e32 v90, 1.0, v90
	v_log_f32_e32 v84, v84
	v_log_f32_e32 v88, v88
	v_max_f32_e32 v2, v68, v68
	v_log_f32_e32 v86, v86
	v_log_f32_e32 v90, v90
	v_max_f32_e32 v85, v69, v69
	v_max_f32_e32 v89, v71, v71
	v_max_f32_e32 v2, 0, v2
	v_add_f32_e32 v92, 1.0, v92
	v_max_f32_e32 v87, v70, v70
	v_max_f32_e32 v91, v72, v72
	v_max_f32_e32 v85, 0, v85
	v_max_f32_e32 v89, 0, v89
	v_log_f32_e32 v92, v92
	v_add_f32_e32 v1, v2, v1
	v_max_f32_e32 v87, 0, v87
	v_max_f32_e32 v91, 0, v91
	v_add_f32_e32 v94, 1.0, v94
	v_add_f32_e32 v2, v85, v84
	v_add_f32_e32 v85, v89, v88
	v_cndmask_b32_e64 v89, 0, -v1, s[10:11]
	v_max_f32_e32 v93, v73, v73
	v_log_f32_e32 v94, v94
	v_add_f32_e32 v84, v87, v86
	v_add_f32_e32 v86, v91, v90
	v_cndmask_b32_e64 v90, 0, -v2, s[12:13]
	v_cndmask_b32_e64 v98, -v1, v89, s[86:87]
	v_max_f32_e32 v93, 0, v93
	v_cndmask_b32_e64 v91, 0, -v84, s[14:15]
	v_cndmask_b32_e64 v90, -v2, v90, s[86:87]
	v_add_f32_e32 v1, 0, v98
	v_max_f32_e32 v95, v74, v74
	v_exp_f32_e64 v96, -|v75|
	v_add_f32_e32 v87, v93, v92
	v_cndmask_b32_e64 v92, 0, -v85, s[16:17]
	v_cndmask_b32_e64 v91, -v84, v91, s[86:87]
	v_add_f32_e32 v1, v90, v1
	v_max_f32_e32 v95, 0, v95
	v_cndmask_b32_e64 v93, 0, -v86, s[18:19]
	v_cndmask_b32_e64 v92, -v85, v92, s[86:87]
	v_add_f32_e32 v1, v91, v1
	v_add_f32_e32 v88, v95, v94
	v_cndmask_b32_e64 v94, 0, -v87, s[20:21]
	v_cndmask_b32_e64 v93, -v86, v93, s[86:87]
	v_add_f32_e32 v1, v92, v1
	v_cndmask_b32_e64 v87, -v87, v94, s[86:87]
	v_add_f32_e32 v1, v93, v1
	v_add_f32_e32 v96, 1.0, v96
	v_add_f32_e32 v86, v87, v1
	v_exp_f32_e64 v1, -|v76|
	v_log_f32_e32 v96, v96
	v_max_f32_e32 v97, v75, v75
	v_max_f32_e32 v97, 0, v97
	v_add_f32_e32 v1, 1.0, v1
	v_add_f32_e32 v2, v97, v96
	v_log_f32_e32 v1, v1
	v_cndmask_b32_e64 v84, 0, -v2, s[24:25]
	v_cndmask_b32_e64 v94, -v2, v84, s[86:87]
	v_max_f32_e32 v2, v76, v76
	v_exp_f32_e64 v84, -|v77|
	v_max_f32_e32 v2, 0, v2
	v_add_f32_e32 v1, v2, v1
	v_cndmask_b32_e64 v2, 0, -v1, s[26:27]
	v_cndmask_b32_e64 v89, -v1, v2, s[86:87]
	v_add_f32_e32 v1, 1.0, v84
	v_log_f32_e32 v1, v1
	v_max_f32_e32 v84, v77, v77
	v_max_f32_e32 v84, 0, v84
	v_add_f32_e32 v2, 0, v89
	v_add_f32_e32 v1, v84, v1
	v_exp_f32_e64 v84, -|v78|
	v_cndmask_b32_e64 v85, 0, -v1, s[28:29]
	v_cndmask_b32_e64 v96, -v1, v85, s[86:87]
	v_add_f32_e32 v1, v96, v2
	v_add_f32_e32 v2, 1.0, v84
	v_log_f32_e32 v2, v2
	v_max_f32_e32 v84, v78, v78
	v_exp_f32_e64 v85, -|v79|
	v_max_f32_e32 v84, 0, v84
	v_add_f32_e32 v2, v84, v2
	v_cndmask_b32_e64 v84, 0, -v2, s[30:31]
	v_cndmask_b32_e64 v97, -v2, v84, s[86:87]
	v_add_f32_e32 v2, 1.0, v85
	v_log_f32_e32 v2, v2
	v_max_f32_e32 v84, v79, v79
	v_max_f32_e32 v84, 0, v84
	v_add_f32_e32 v1, v97, v1
	v_add_f32_e32 v2, v84, v2
	v_exp_f32_e64 v84, -|v80|
	v_cndmask_b32_e64 v85, 0, -v2, s[34:35]
	v_cndmask_b32_e64 v99, -v2, v85, s[86:87]
	v_exp_f32_e64 v85, -|v81|
	v_add_f32_e32 v2, 1.0, v84
	v_log_f32_e32 v2, v2
	v_max_f32_e32 v84, v80, v80
	v_max_f32_e32 v84, 0, v84
	v_add_f32_e32 v1, v99, v1
	v_add_f32_e32 v2, v84, v2
	v_cndmask_b32_e64 v84, 0, -v2, s[36:37]
	v_cndmask_b32_e64 v100, -v2, v84, s[86:87]
	v_add_f32_e32 v2, 1.0, v85
	v_log_f32_e32 v2, v2
	v_max_f32_e32 v84, v81, v81
	v_max_f32_e32 v84, 0, v84
	v_add_f32_e32 v1, v100, v1
	v_add_f32_e32 v2, v84, v2
	v_exp_f32_e64 v84, -|v82|
	v_cndmask_b32_e64 v85, 0, -v2, s[38:39]
	v_cndmask_b32_e64 v101, -v2, v85, s[86:87]
	v_exp_f32_e64 v85, -|v83|
	v_add_f32_e32 v2, 1.0, v84
	v_log_f32_e32 v2, v2
	v_max_f32_e32 v84, v82, v82
	v_max_f32_e32 v84, 0, v84
	v_add_f32_e32 v1, v101, v1
	v_add_f32_e32 v2, v84, v2
	v_cndmask_b32_e64 v84, 0, -v2, s[40:41]
	v_cndmask_b32_e64 v102, -v2, v84, s[86:87]
	v_add_f32_e32 v2, 1.0, v85
	v_log_f32_e32 v2, v2
	v_max_f32_e32 v84, v83, v83
	v_max_f32_e32 v84, 0, v84
	v_add_f32_e32 v1, v102, v1
	v_add_f32_e32 v2, v84, v2
	v_cndmask_b32_e64 v84, 0, -v2, s[42:43]
	v_cndmask_b32_e64 v2, -v2, v84, s[86:87]
	v_add_f32_e32 v84, v2, v1
	v_mov_b32_e32 v1, v84
	v_mov_b32_e32 v85, v84
	s_nop 1
	v_permlane32_swap_b32_e32 v1, v85
	v_cndmask_b32_e64 v85, v1, v85, s[2:3]
	v_add_f32_e32 v1, v173, v85
	v_cndmask_b32_e64 v103, v173, v1, s[6:7]
	v_add_f32_e32 v105, v1, v84
	v_add_f32_e32 v1, v83, v2
	v_add_f32_e32 v83, v103, v2
	v_add_f32_e32 v2, v82, v102
	v_add_f32_e32 v82, v102, v83
	v_add_f32_e32 v81, v81, v101
	v_add_f32_e32 v81, v81, v82
	v_add_f32_e32 v82, v101, v82
	v_add_f32_e32 v80, v80, v100
	v_add_f32_e32 v80, v80, v82
	v_add_f32_e32 v82, v100, v82
	v_add_f32_e32 v79, v79, v99
	v_add_f32_e32 v79, v79, v82
	v_add_f32_e32 v82, v99, v82
	v_add_f32_e32 v78, v78, v97
	v_cndmask_b32_e64 v95, 0, -v88, s[22:23]
	v_add_f32_e32 v78, v78, v82
	v_add_f32_e32 v82, v97, v82
	v_add_f32_e32 v77, v77, v96
	v_add_f32_e32 v77, v77, v82
	v_add_f32_e32 v82, v96, v82
	v_add_f32_e32 v76, v76, v89
	v_cndmask_b32_e64 v88, -v88, v95, s[86:87]
	v_add_f32_e32 v76, v76, v82
	v_add_f32_e32 v82, v88, v86
	v_add_f32_e32 v82, v94, v82
	v_mov_b32_e32 v86, v82
	v_mov_b32_e32 v89, v82
	s_nop 1
	v_permlane32_swap_b32_e32 v86, v89
	v_add_f32_e32 v104, v173, v84
	v_cndmask_b32_e64 v86, v86, v89, s[2:3]
	v_add_f32_e32 v2, v83, v2
	v_add_f32_e32 v83, v104, v85
	v_add_f32_e32 v89, v105, v86
	v_add_f32_e32 v75, v75, v94
	v_cndmask_b32_e64 v89, v83, v89, s[6:7]
	v_add_f32_e32 v75, v75, v89
	v_exp_f32_e32 v83, v75
	v_mov_b32_e32 v75, v94
	v_pk_add_f32 v[74:75], v[74:75], v[88:89]
	v_add_f32_e32 v73, v73, v87
	v_add_f32_e32 v74, v74, v75
	v_add_f32_e32 v75, v88, v75
	v_add_f32_e32 v73, v73, v75
	v_add_f32_e32 v75, v87, v75
	v_add_f32_e32 v72, v72, v93
	v_add_f32_e32 v72, v72, v75
	v_add_f32_e32 v75, v93, v75
	v_add_f32_e32 v71, v71, v92
	v_add_f32_e32 v71, v71, v75
	v_add_f32_e32 v75, v92, v75
	v_add_f32_e32 v70, v70, v91
	v_add_f32_e32 v70, v70, v75
	v_add_f32_e32 v75, v91, v75
	v_add_f32_e32 v69, v69, v90
	v_add_f32_e32 v69, v69, v75
	v_add_f32_e32 v75, v90, v75
	v_add_f32_e32 v68, v68, v98
	v_add_f32_e32 v1, v103, v1
	v_add_f32_e32 v68, v68, v75
	v_exp_f32_e32 v1, v1
	v_exp_f32_e32 v2, v2
	v_exp_f32_e32 v81, v81
	v_exp_f32_e32 v80, v80
	v_exp_f32_e32 v79, v79
	v_exp_f32_e32 v78, v78
	v_exp_f32_e32 v77, v77
	v_exp_f32_e32 v76, v76
	v_exp_f32_e32 v74, v74
	v_exp_f32_e32 v73, v73
	v_exp_f32_e32 v72, v72
	v_exp_f32_e32 v71, v71
	v_exp_f32_e32 v70, v70
	v_exp_f32_e32 v69, v69
	v_exp_f32_e32 v68, v68
	s_cbranch_scc1 .LBB0_392
	s_or_b64 vcc, s[12:13], s[10:11]
	v_cndmask_b32_e32 v68, 0, v68, vcc
	s_or_b64 vcc, s[16:17], s[14:15]
	v_cndmask_b32_e32 v70, 0, v70, vcc
	s_or_b64 vcc, s[20:21], s[18:19]
	v_cndmask_b32_e32 v72, 0, v72, vcc
	s_or_b64 vcc, s[24:25], s[22:23]
	v_cndmask_b32_e32 v74, 0, v74, vcc
	s_or_b64 vcc, s[28:29], s[26:27]
	v_cndmask_b32_e32 v76, 0, v76, vcc
	s_or_b64 vcc, s[34:35], s[30:31]
	v_cndmask_b32_e32 v78, 0, v78, vcc
	s_or_b64 vcc, s[38:39], s[36:37]
	v_cndmask_b32_e32 v80, 0, v80, vcc
	s_or_b64 vcc, s[42:43], s[40:41]
	v_cndmask_b32_e64 v69, 0, v69, s[12:13]
	v_cndmask_b32_e64 v71, 0, v71, s[16:17]
	v_cndmask_b32_e64 v73, 0, v73, s[20:21]
	v_cndmask_b32_e64 v83, 0, v83, s[24:25]
	v_cndmask_b32_e64 v77, 0, v77, s[28:29]
	v_cndmask_b32_e64 v79, 0, v79, s[34:35]
	v_cndmask_b32_e64 v81, 0, v81, s[38:39]
	v_cndmask_b32_e64 v1, 0, v1, s[42:43]
	v_cndmask_b32_e32 v2, 0, v2, vcc
.LBB0_392:
	v_cvt_pk_bf16_f32 v217, v2, v1
	v_add_u32_e32 v1, s90, v180
	v_add_u32_e32 v2, s90, v167
	v_add_f32_e32 v75, v82, v84
	v_add_f32_e32 v82, v85, v86
	ds_read_b64_tr_b16 v[84:85], v1 offset:8192
	ds_read_b64_tr_b16 v[86:87], v2 offset:9216
	v_add_u32_e32 v222, s90, v191
	v_add_u32_e32 v223, s90, v192
	v_add_u32_e32 v224, s90, v193
	v_add_u32_e32 v225, s90, v194
	v_add_u32_e32 v226, s90, v195
	v_add_u32_e32 v227, s90, v196
	ds_read_b64_tr_b16 v[100:101], v222 offset:8192
	ds_read_b64_tr_b16 v[102:103], v223 offset:8192
	ds_read_b64_tr_b16 v[116:117], v224 offset:8192
	ds_read_b64_tr_b16 v[118:119], v225 offset:8192
	ds_read_b64_tr_b16 v[218:219], v226 offset:8192
	ds_read_b64_tr_b16 v[220:221], v227 offset:8192
	v_add_f32_e32 v75, v82, v75
	v_cvt_pk_bf16_f32 v210, v68, v69
	v_cvt_pk_bf16_f32 v211, v70, v71
	v_cvt_pk_bf16_f32 v212, v72, v73
	v_cvt_pk_bf16_f32 v213, v74, v83
	v_add_f32_e32 v173, v173, v75
	v_cvt_pk_bf16_f32 v214, v76, v77
	v_cvt_pk_bf16_f32 v215, v78, v79
	v_cvt_pk_bf16_f32 v216, v80, v81
	s_waitcnt lgkmcnt(6)
	v_mfma_f32_32x32x16_bf16 v[36:51], v[84:87], v[210:213], v[36:51]
	s_cmp_eq_u32 s1, 0
	s_waitcnt lgkmcnt(4)
	v_mfma_f32_32x32x16_bf16 v[52:67], v[100:103], v[210:213], v[52:67]
	s_waitcnt lgkmcnt(2)
	v_mfma_f32_32x32x16_bf16 v[20:35], v[116:119], v[210:213], v[20:35]
	s_waitcnt lgkmcnt(0)
	v_mfma_f32_32x32x16_bf16 v[4:19], v[218:221], v[210:213], v[4:19]
	ds_read_b64_tr_b16 v[210:211], v1 offset:12288
	ds_read_b64_tr_b16 v[212:213], v2 offset:13312
	s_waitcnt lgkmcnt(0)
	v_mfma_f32_32x32x16_bf16 v[36:51], v[210:213], v[214:217], v[36:51]
	ds_read_b64_tr_b16 v[210:211], v222 offset:12288
	ds_read_b64_tr_b16 v[212:213], v223 offset:12288
	s_waitcnt lgkmcnt(0)
	v_mfma_f32_32x32x16_bf16 v[52:67], v[210:213], v[214:217], v[52:67]
	ds_read_b64_tr_b16 v[210:211], v224 offset:12288
	ds_read_b64_tr_b16 v[212:213], v225 offset:12288
	s_waitcnt lgkmcnt(0)
	v_mfma_f32_32x32x16_bf16 v[20:35], v[210:213], v[214:217], v[20:35]
	ds_read_b64_tr_b16 v[210:211], v226 offset:12288
	ds_read_b64_tr_b16 v[212:213], v227 offset:12288
	s_waitcnt lgkmcnt(0)
	v_mfma_f32_32x32x16_bf16 v[4:19], v[210:213], v[214:217], v[4:19]
	s_cbranch_scc1 .LBB0_395
	v_cmp_lt_f32_e32 vcc, s5, v173
	s_cmp_eq_u64 vcc, 0
	s_cselect_b64 s[86:87], -1, 0
	s_and_saveexec_b64 s[90:91], s[8:9]
	s_cbranch_execz .LBB0_386
	s_branch .LBB0_396
.LBB0_394:
	s_and_saveexec_b64 s[90:91], s[8:9]
	s_cbranch_execz .LBB0_386
	s_branch .LBB0_396

.LBB0_401:
	ds_read_b64_tr_b16 v[226:227], v242 offset:12288
	ds_read_b64_tr_b16 v[228:229], v243 offset:13312
	ds_read_b64_tr_b16 v[230:231], v244 offset:12288
	ds_read_b64_tr_b16 v[232:233], v245 offset:12288
	ds_read_b64_tr_b16 v[234:235], v246 offset:12288
	ds_read_b64_tr_b16 v[236:237], v247 offset:12288
	ds_read_b64_tr_b16 v[238:239], v248 offset:12288
	ds_read_b64_tr_b16 v[240:241], v249 offset:12288
	v_sub_f32_e32 v5, v82, v8
	v_exp_f32_e32 v5, v5
	v_sub_f32_e32 v7, v83, v8
	v_exp_f32_e32 v7, v7
	v_and_b32_e32 v6, 1, v4
	v_cmp_eq_u32_e32 vcc, 1, v6
	v_and_b32_e32 v9, 2, v4
	v_and_b32_e32 v10, 4, v4
	v_cndmask_b32_e32 v5, 0, v5, vcc
	v_cmp_ne_u32_e32 vcc, 0, v9
	v_sub_f32_e32 v9, v84, v8
	v_exp_f32_e32 v9, v9
	v_cndmask_b32_e32 v7, 0, v7, vcc
	v_cmp_ne_u32_e32 vcc, 0, v10
	v_sub_f32_e32 v10, v85, v8
	v_exp_f32_e32 v10, v10
	v_and_b32_e32 v11, 8, v4
	v_cndmask_b32_e32 v9, 0, v9, vcc
	v_cmp_ne_u32_e32 vcc, 0, v11
	v_and_b32_e32 v12, 16, v4
	v_and_b32_e32 v13, 32, v4
	v_cndmask_b32_e32 v11, 0, v10, vcc
	v_sub_f32_e32 v10, v86, v8
	v_exp_f32_e32 v10, v10
	v_cmp_ne_u32_e32 vcc, 0, v12
	v_and_b32_e32 v14, 64, v4
	v_and_b32_e32 v15, 0x80, v4
	v_cndmask_b32_e32 v12, 0, v10, vcc
	v_sub_f32_e32 v10, v87, v8
	v_exp_f32_e32 v10, v10
	v_cmp_ne_u32_e32 vcc, 0, v13
	v_and_b32_e32 v16, 0x100, v4
	v_and_b32_e32 v17, 0x200, v4
	v_cndmask_b32_e32 v13, 0, v10, vcc
	v_sub_f32_e32 v10, v88, v8
	v_exp_f32_e32 v10, v10
	v_cmp_ne_u32_e32 vcc, 0, v14
	v_and_b32_e32 v82, 0x400, v4
	v_and_b32_e32 v83, 0x800, v4
	v_cndmask_b32_e32 v14, 0, v10, vcc
	v_sub_f32_e32 v10, v89, v8
	v_exp_f32_e32 v10, v10
	v_cmp_ne_u32_e32 vcc, 0, v15
	v_and_b32_e32 v84, 0x1000, v4
	v_add_f32_e32 v6, 0, v5
	v_cndmask_b32_e32 v15, 0, v10, vcc
	v_sub_f32_e32 v10, v90, v8
	v_exp_f32_e32 v10, v10
	v_cmp_ne_u32_e32 vcc, 0, v16
	v_add_f32_e32 v6, v7, v6
	v_add_f32_e32 v6, v9, v6
	v_cndmask_b32_e32 v16, 0, v10, vcc
	v_sub_f32_e32 v10, v91, v8
	v_exp_f32_e32 v10, v10
	v_cmp_ne_u32_e32 vcc, 0, v17
	v_and_b32_e32 v85, 0x2000, v4
	v_add_f32_e32 v6, v11, v6
	v_cndmask_b32_e32 v17, 0, v10, vcc
	v_sub_f32_e32 v10, v92, v8
	v_exp_f32_e32 v10, v10
	v_cmp_ne_u32_e32 vcc, 0, v82
	v_add_f32_e32 v6, v12, v6
	v_add_f32_e32 v6, v13, v6
	v_cndmask_b32_e32 v82, 0, v10, vcc
	v_sub_f32_e32 v10, v93, v8
	v_exp_f32_e32 v10, v10
	v_cmp_ne_u32_e32 vcc, 0, v83
	v_add_f32_e32 v6, v14, v6
	v_add_f32_e32 v6, v15, v6
	v_cndmask_b32_e32 v83, 0, v10, vcc
	v_sub_f32_e32 v10, v94, v8
	v_exp_f32_e32 v10, v10
	v_cmp_ne_u32_e32 vcc, 0, v84
	v_and_b32_e32 v86, 0x4000, v4
	v_add_f32_e32 v6, v16, v6
	v_cndmask_b32_e32 v84, 0, v10, vcc
	v_sub_f32_e32 v10, v95, v8
	v_exp_f32_e32 v10, v10
	v_cmp_ne_u32_e32 vcc, 0, v85
	v_add_f32_e32 v6, v17, v6
	v_add_f32_e32 v6, v82, v6
	v_cndmask_b32_e32 v85, 0, v10, vcc
	v_sub_f32_e32 v10, v96, v8
	v_exp_f32_e32 v10, v10
	v_cmp_ne_u32_e32 vcc, 0, v86
	v_add_f32_e32 v6, v83, v6
	v_add_f32_e32 v6, v84, v6
	v_cndmask_b32_e32 v86, 0, v10, vcc
	v_sub_f32_e32 v10, v97, v8
	v_exp_f32_e32 v10, v10
	v_and_b32_e32 v4, 0x8000, v4
	v_add_f32_e32 v6, v85, v6
	v_cmp_ne_u32_e32 vcc, 0, v4
	v_add_f32_e32 v6, v86, v6
	v_cvt_pk_bf16_f32 v11, v9, v11
	v_cndmask_b32_e32 v87, 0, v10, vcc
	v_add_f32_e32 v88, v87, v6
	v_fmac_f32_e32 v88, v133, v2
	v_cvt_pk_bf16_f32 v12, v12, v13
	v_cvt_pk_bf16_f32 v13, v14, v15
	v_cvt_pk_bf16_f32 v4, v16, v17
	v_cvt_pk_bf16_f32 v10, v5, v7
	v_cvt_pk_bf16_f32 v5, v82, v83
	v_cvt_pk_bf16_f32 v6, v84, v85
	v_cvt_pk_bf16_f32 v7, v86, v87
	v_mov_b32_e32 v133, v88
	v_mov_b32_e32 v138, v8
	s_waitcnt lgkmcnt(0)
	v_mfma_f32_32x32x16_bf16 v[66:81], v[210:213], v[10:13], v[66:81]
	v_mfma_f32_32x32x16_bf16 v[50:65], v[214:217], v[10:13], v[50:65]
	v_mfma_f32_32x32x16_bf16 v[34:49], v[218:221], v[10:13], v[34:49]
	v_mfma_f32_32x32x16_bf16 v[18:33], v[222:225], v[10:13], v[18:33]
	v_mfma_f32_32x32x16_bf16 v[66:81], v[226:229], v[4:7], v[66:81]
	v_mfma_f32_32x32x16_bf16 v[50:65], v[230:233], v[4:7], v[50:65]
	v_mfma_f32_32x32x16_bf16 v[34:49], v[234:237], v[4:7], v[34:49]
	v_mfma_f32_32x32x16_bf16 v[18:33], v[238:241], v[4:7], v[18:33]

.LBB0_403:
	s_add_i32 s0, s86, s4
	s_add_i32 s1, s0, 4
	s_max_i32 s1, s1, s90
	s_add_i32 s46, s69, 0xc000
	s_and_b32 s46, s46, 0xc000
	s_lshl_b32 s76, s1, 5
	s_waitcnt vmcnt(4)
	s_lshl_b64 s[66:67], s[76:77], 11
	s_add_i32 s1, s94, s46
	s_waitcnt lgkmcnt(0)
	s_barrier
	v_lshl_add_u64 v[4:5], v[134:135], 0, s[66:67]
	s_mov_b32 m0, s1
	s_nop 0
	global_load_lds_dwordx4 v[4:5], off
	v_lshl_add_u64 v[4:5], v[136:137], 0, s[66:67]
	s_add_i32 m0, s1, 0x2000
	s_add_i32 s1, s0, 7
	global_load_lds_dwordx4 v[4:5], off
	s_cmp_gt_i32 s1, s87
	s_cbranch_scc1 .LBB0_402
	s_add_i32 s0, s0, 11
	s_cmp_lt_i32 s0, s87
	s_cbranch_scc1 .LBB0_402
	s_and_b32 s0, s69, 0xc000
	s_add_i32 s46, s0, 0
	v_add_u32_e32 v2, s46, v181
	v_add_u32_e32 v4, v2, v183
	v_add_u32_e32 v5, v2, v184
	v_add_u32_e32 v6, v2, v185
	v_add_u32_e32 v7, v2, v186
	ds_read_b128 v[210:213], v4
	ds_read_b128 v[214:217], v5
	ds_read_b128 v[218:221], v6
	ds_read_b128 v[222:225], v7
	v_add_u32_e32 v8, v2, v187
	v_add_u32_e32 v9, v2, v188
	v_add_u32_e32 v10, v2, v189
	v_add_u32_e32 v11, v2, v190
	ds_read_b128 v[226:229], v8
	ds_read_b128 v[230:233], v9
	ds_read_b128 v[234:237], v10
	ds_read_b128 v[238:241], v11
	s_cmp_eq_u32 s92, s4
	s_cselect_b64 s[0:1], -1, 0
	s_cmp_eq_u32 s47, s4
	s_cselect_b64 s[66:67], -1, 0
	s_or_b64 s[66:67], s[0:1], s[66:67]
	s_mov_b64 s[0:1], -1
	s_and_b64 vcc, exec, s[66:67]
	v_add_u32_e32 v242, s46, v180
	v_add_u32_e32 v243, s46, v167
	v_add_u32_e32 v244, s46, v191
	v_add_u32_e32 v245, s46, v192
	v_add_u32_e32 v246, s46, v193
	v_add_u32_e32 v247, s46, v194
	v_add_u32_e32 v248, s46, v195
	v_add_u32_e32 v249, s46, v196
	s_waitcnt lgkmcnt(7)
	v_mfma_f32_32x32x16_bf16 v[82:97], v[210:213], v[98:101], 0
	s_waitcnt lgkmcnt(6)
	v_mfma_f32_32x32x16_bf16 v[82:97], v[214:217], v[102:105], v[82:97]
	s_waitcnt lgkmcnt(5)
	v_mfma_f32_32x32x16_bf16 v[82:97], v[218:221], v[106:109], v[82:97]
	s_waitcnt lgkmcnt(4)
	v_mfma_f32_32x32x16_bf16 v[82:97], v[222:225], v[110:113], v[82:97]
	s_waitcnt lgkmcnt(3)
	v_mfma_f32_32x32x16_bf16 v[82:97], v[226:229], v[114:117], v[82:97]
	s_waitcnt lgkmcnt(2)
	v_mfma_f32_32x32x16_bf16 v[82:97], v[230:233], v[118:121], v[82:97]
	s_waitcnt lgkmcnt(1)
	v_mfma_f32_32x32x16_bf16 v[82:97], v[234:237], v[122:125], v[82:97]
	s_waitcnt lgkmcnt(0)
	v_mfma_f32_32x32x16_bf16 v[82:97], v[238:241], v[126:129], v[82:97]
	ds_read_b64_tr_b16 v[210:211], v242 offset:8192
	ds_read_b64_tr_b16 v[212:213], v243 offset:9216
	ds_read_b64_tr_b16 v[214:215], v244 offset:8192
	ds_read_b64_tr_b16 v[216:217], v245 offset:8192
	ds_read_b64_tr_b16 v[218:219], v246 offset:8192
	ds_read_b64_tr_b16 v[220:221], v247 offset:8192
	ds_read_b64_tr_b16 v[222:223], v248 offset:8192
	ds_read_b64_tr_b16 v[224:225], v249 offset:8192
	s_nop 3
	s_cbranch_vccnz .LBB0_407
	v_max3_f32 v2, v82, s80, v83
	v_max3_f32 v2, v2, v84, v85
	v_max3_f32 v2, v2, v86, v87
	v_max3_f32 v2, v2, v88, v89
	v_max3_f32 v2, v2, v90, v91
	v_max3_f32 v2, v2, v92, v93
	v_max3_f32 v2, v2, v94, v95
	v_max3_f32 v2, v2, v96, v97
	s_mov_b64 s[0:1], 0
